# P6 output-GEMM epilogue: residual loads rolled two rounds ahead with counted vmcnt and scalar row bases
# speedup vs baseline: 1.0089x; 1.0089x over previous
.LBB0_504:
	v_or_b32_e32 v130, 0x10000, v163
	v_add_u32_e32 v134, 0x10400, v163
	v_add_u32_e32 v150, 0x10800, v163
	v_add_u32_e32 v154, 0x10c00, v163
	ds_read_b128 v[130:133], v130
	ds_read_b128 v[134:137], v134
	ds_read_b128 v[150:153], v150
	ds_read_b128 v[154:157], v154
	s_add_u32 s10, s52, 0xfff80080
	s_addc_u32 s11, s53, -1
	s_cmp_eq_u32 s29, 28
	s_cselect_b32 s11, s9, s11
	s_cselect_b32 s10, s8, s10
	s_cselect_b32 s55, s35, s7
	s_cselect_b32 s54, s34, s5
	v_lshl_add_u64 v[206:207], s[52:53], 0, v[146:147]
	s_add_i32 m0, s42, 0xc000
	ds_read_b128 v[158:161], v162
	ds_read_b128 v[166:169], v162 offset:1024
	ds_read_b128 v[170:173], v162 offset:2048
	ds_read_b128 v[174:177], v162 offset:3072
	ds_read_b128 v[178:181], v162 offset:4096
	ds_read_b128 v[182:185], v162 offset:5120
	ds_read_b128 v[186:189], v162 offset:6144
	ds_read_b128 v[190:193], v162 offset:7168
	global_load_lds_dwordx4 v[206:207], off
	v_lshl_add_u64 v[206:207], s[52:53], 0, v[148:149]
	s_add_i32 m0, s42, 0xe000
	s_nop 0
	global_load_lds_dwordx4 v[206:207], off
	s_waitcnt lgkmcnt(8)
	s_barrier
	s_waitcnt lgkmcnt(0)
	s_setprio 1
	s_waitcnt lgkmcnt(0)
	v_mfma_f32_16x16x32_bf16 v[126:129], v[130:133], v[158:161], v[126:129]
	v_mfma_f32_16x16x32_bf16 v[122:125], v[150:153], v[158:161], v[122:125]
	v_mfma_f32_16x16x32_bf16 v[118:121], v[130:133], v[170:173], v[118:121]
	v_mfma_f32_16x16x32_bf16 v[114:117], v[150:153], v[170:173], v[114:117]
	v_mfma_f32_16x16x32_bf16 v[110:113], v[130:133], v[178:181], v[110:113]
	v_mfma_f32_16x16x32_bf16 v[106:109], v[150:153], v[178:181], v[106:109]
	v_mfma_f32_16x16x32_bf16 v[102:105], v[130:133], v[186:189], v[102:105]
	v_mfma_f32_16x16x32_bf16 v[98:101], v[150:153], v[186:189], v[98:101]
	v_mfma_f32_16x16x32_bf16 v[126:129], v[134:137], v[166:169], v[126:129]
	v_mfma_f32_16x16x32_bf16 v[122:125], v[154:157], v[166:169], v[122:125]
	v_mfma_f32_16x16x32_bf16 v[118:121], v[134:137], v[174:177], v[118:121]
	v_mfma_f32_16x16x32_bf16 v[114:117], v[154:157], v[174:177], v[114:117]
	v_mfma_f32_16x16x32_bf16 v[110:113], v[134:137], v[182:185], v[110:113]
	v_mfma_f32_16x16x32_bf16 v[106:109], v[154:157], v[182:185], v[106:109]
	v_mfma_f32_16x16x32_bf16 v[102:105], v[134:137], v[190:193], v[102:105]
	v_mfma_f32_16x16x32_bf16 v[98:101], v[154:157], v[190:193], v[98:101]
	s_setprio 0
	s_barrier
	v_or_b32_e32 v165, 0x14000, v163
	s_mov_b32 m0, s41
	v_add_u32_e32 v197, 0x14400, v163
	ds_read_b128 v[206:209], v165
	ds_read_b128 v[210:213], v197
	v_add_u32_e32 v165, 0x14800, v163
	v_lshl_add_u64 v[222:223], s[54:55], 0, v[194:195]
	v_add_u32_e32 v197, 0x14c00, v163
	ds_read_b128 v[214:217], v165
	ds_read_b128 v[218:221], v197
	global_load_lds_dwordx4 v[222:223], off
	v_lshl_add_u64 v[224:225], s[54:55], 0, v[138:139]
	s_mov_b32 m0, s57
	s_nop 0
	global_load_lds_dwordx4 v[224:225], off
	s_barrier
	s_waitcnt lgkmcnt(0)
	s_setprio 1
	s_waitcnt lgkmcnt(0)
	v_mfma_f32_16x16x32_bf16 v[62:65], v[206:209], v[158:161], v[62:65]
	v_mfma_f32_16x16x32_bf16 v[58:61], v[214:217], v[158:161], v[58:61]
	v_mfma_f32_16x16x32_bf16 v[54:57], v[206:209], v[170:173], v[54:57]
	v_mfma_f32_16x16x32_bf16 v[46:49], v[214:217], v[170:173], v[46:49]
	v_mfma_f32_16x16x32_bf16 v[50:53], v[206:209], v[178:181], v[50:53]
	v_mfma_f32_16x16x32_bf16 v[42:45], v[214:217], v[178:181], v[42:45]
	v_mfma_f32_16x16x32_bf16 v[38:41], v[206:209], v[186:189], v[38:41]
	v_mfma_f32_16x16x32_bf16 v[34:37], v[214:217], v[186:189], v[34:37]
	v_mfma_f32_16x16x32_bf16 v[62:65], v[210:213], v[166:169], v[62:65]
	v_mfma_f32_16x16x32_bf16 v[58:61], v[218:221], v[166:169], v[58:61]
	v_mfma_f32_16x16x32_bf16 v[54:57], v[210:213], v[174:177], v[54:57]
	v_mfma_f32_16x16x32_bf16 v[46:49], v[218:221], v[174:177], v[46:49]
	v_mfma_f32_16x16x32_bf16 v[50:53], v[210:213], v[182:185], v[50:53]
	v_mfma_f32_16x16x32_bf16 v[42:45], v[218:221], v[182:185], v[42:45]
	v_mfma_f32_16x16x32_bf16 v[38:41], v[210:213], v[190:193], v[38:41]
	v_mfma_f32_16x16x32_bf16 v[34:37], v[218:221], v[190:193], v[34:37]
	s_setprio 0
	s_mov_b32 m0, s42
	v_lshl_add_u64 v[226:227], s[10:11], 0, v[142:143]
	s_barrier
	ds_read_b128 v[158:161], v162 offset:16384
	ds_read_b128 v[166:169], v162 offset:17408
	ds_read_b128 v[170:173], v162 offset:18432
	ds_read_b128 v[174:177], v162 offset:19456
	ds_read_b128 v[178:181], v162 offset:20480
	ds_read_b128 v[182:185], v162 offset:21504
	ds_read_b128 v[186:189], v162 offset:22528
	ds_read_b128 v[190:193], v162 offset:23552
	global_load_lds_dwordx4 v[226:227], off
	v_lshl_add_u64 v[228:229], s[10:11], 0, v[140:141]
	s_mov_b32 m0, s58
	s_nop 0
	global_load_lds_dwordx4 v[228:229], off
	s_barrier
	s_waitcnt lgkmcnt(0)
	s_setprio 1
	s_waitcnt lgkmcnt(0)
	v_mfma_f32_16x16x32_bf16 v[94:97], v[130:133], v[158:161], v[94:97]
	v_mfma_f32_16x16x32_bf16 v[90:93], v[150:153], v[158:161], v[90:93]
	v_mfma_f32_16x16x32_bf16 v[86:89], v[130:133], v[170:173], v[86:89]
	v_mfma_f32_16x16x32_bf16 v[82:85], v[150:153], v[170:173], v[82:85]
	v_mfma_f32_16x16x32_bf16 v[78:81], v[130:133], v[178:181], v[78:81]
	v_mfma_f32_16x16x32_bf16 v[74:77], v[150:153], v[178:181], v[74:77]
	v_mfma_f32_16x16x32_bf16 v[70:73], v[130:133], v[186:189], v[70:73]
	v_mfma_f32_16x16x32_bf16 v[66:69], v[150:153], v[186:189], v[66:69]
	v_mfma_f32_16x16x32_bf16 v[94:97], v[134:137], v[166:169], v[94:97]
	v_mfma_f32_16x16x32_bf16 v[90:93], v[154:157], v[166:169], v[90:93]
	v_mfma_f32_16x16x32_bf16 v[86:89], v[134:137], v[174:177], v[86:89]
	v_mfma_f32_16x16x32_bf16 v[82:85], v[154:157], v[174:177], v[82:85]
	v_mfma_f32_16x16x32_bf16 v[78:81], v[134:137], v[182:185], v[78:81]
	v_mfma_f32_16x16x32_bf16 v[74:77], v[154:157], v[182:185], v[74:77]
	v_mfma_f32_16x16x32_bf16 v[70:73], v[134:137], v[190:193], v[70:73]
	v_mfma_f32_16x16x32_bf16 v[66:69], v[154:157], v[190:193], v[66:69]
	s_setprio 0
	s_barrier
	s_add_u32 s86, s54, 0x80000
	s_addc_u32 s87, s55, 0
	s_mov_b32 m0, s59
	v_lshl_add_u64 v[130:131], s[86:87], 0, v[194:195]
	global_load_lds_dwordx4 v[130:131], off
	v_lshl_add_u64 v[130:131], s[86:87], 0, v[138:139]
	s_mov_b32 m0, s60
	s_nop 0
	global_load_lds_dwordx4 v[130:131], off
	s_waitcnt vmcnt(6)
	s_barrier
	s_setprio 1
	v_mfma_f32_16x16x32_bf16 v[30:33], v[206:209], v[158:161], v[30:33]
	v_mfma_f32_16x16x32_bf16 v[18:21], v[214:217], v[158:161], v[18:21]
	v_mfma_f32_16x16x32_bf16 v[26:29], v[206:209], v[170:173], v[26:29]
	v_mfma_f32_16x16x32_bf16 v[14:17], v[214:217], v[170:173], v[14:17]
	v_mfma_f32_16x16x32_bf16 v[22:25], v[206:209], v[178:181], v[22:25]
	v_mfma_f32_16x16x32_bf16 v[6:9], v[214:217], v[178:181], v[6:9]
	v_mfma_f32_16x16x32_bf16 v[10:13], v[206:209], v[186:189], v[10:13]
	v_mfma_f32_16x16x32_bf16 v[2:5], v[214:217], v[186:189], v[2:5]
	v_mfma_f32_16x16x32_bf16 v[30:33], v[210:213], v[166:169], v[30:33]
	v_mfma_f32_16x16x32_bf16 v[18:21], v[218:221], v[166:169], v[18:21]
	v_mfma_f32_16x16x32_bf16 v[26:29], v[210:213], v[174:177], v[26:29]
	v_mfma_f32_16x16x32_bf16 v[14:17], v[218:221], v[174:177], v[14:17]
	v_mfma_f32_16x16x32_bf16 v[22:25], v[210:213], v[182:185], v[22:25]
	v_mfma_f32_16x16x32_bf16 v[6:9], v[218:221], v[182:185], v[6:9]
	v_mfma_f32_16x16x32_bf16 v[10:13], v[210:213], v[190:193], v[10:13]
	v_mfma_f32_16x16x32_bf16 v[2:5], v[218:221], v[190:193], v[2:5]
	s_setprio 0
	v_or_b32_e32 v130, 0x18000, v163
	v_add_u32_e32 v134, 0x18400, v163
	v_add_u32_e32 v150, 0x18800, v163
	v_add_u32_e32 v154, 0x18c00, v163
	s_barrier
	ds_read_b128 v[130:133], v130
	ds_read_b128 v[134:137], v134
	ds_read_b128 v[150:153], v150
	ds_read_b128 v[154:157], v154
	s_add_u32 s10, s10, 0x80000
	s_addc_u32 s11, s11, 0
	s_mov_b32 m0, s61
	v_lshl_add_u64 v[206:207], s[10:11], 0, v[142:143]
	ds_read_b128 v[158:161], v162 offset:32768
	ds_read_b128 v[166:169], v162 offset:33792
	ds_read_b128 v[170:173], v162 offset:34816
	ds_read_b128 v[174:177], v162 offset:35840
	ds_read_b128 v[178:181], v162 offset:36864
	ds_read_b128 v[182:185], v162 offset:37888
	ds_read_b128 v[186:189], v162 offset:38912
	ds_read_b128 v[190:193], v162 offset:39936
	global_load_lds_dwordx4 v[206:207], off
	v_lshl_add_u64 v[206:207], s[10:11], 0, v[140:141]
	s_mov_b32 m0, s62
	s_nop 0
	global_load_lds_dwordx4 v[206:207], off
	s_waitcnt lgkmcnt(8)
	s_barrier
	s_waitcnt lgkmcnt(0)
	s_setprio 1
	s_waitcnt lgkmcnt(0)
	v_mfma_f32_16x16x32_bf16 v[126:129], v[130:133], v[158:161], v[126:129]
	v_mfma_f32_16x16x32_bf16 v[122:125], v[150:153], v[158:161], v[122:125]
	v_mfma_f32_16x16x32_bf16 v[118:121], v[130:133], v[170:173], v[118:121]
	v_mfma_f32_16x16x32_bf16 v[114:117], v[150:153], v[170:173], v[114:117]
	v_mfma_f32_16x16x32_bf16 v[110:113], v[130:133], v[178:181], v[110:113]
	v_mfma_f32_16x16x32_bf16 v[106:109], v[150:153], v[178:181], v[106:109]
	v_mfma_f32_16x16x32_bf16 v[102:105], v[130:133], v[186:189], v[102:105]
	v_mfma_f32_16x16x32_bf16 v[98:101], v[150:153], v[186:189], v[98:101]
	v_mfma_f32_16x16x32_bf16 v[126:129], v[134:137], v[166:169], v[126:129]
	v_mfma_f32_16x16x32_bf16 v[122:125], v[154:157], v[166:169], v[122:125]
	v_mfma_f32_16x16x32_bf16 v[118:121], v[134:137], v[174:177], v[118:121]
	v_mfma_f32_16x16x32_bf16 v[114:117], v[154:157], v[174:177], v[114:117]
	v_mfma_f32_16x16x32_bf16 v[110:113], v[134:137], v[182:185], v[110:113]
	v_mfma_f32_16x16x32_bf16 v[106:109], v[154:157], v[182:185], v[106:109]
	v_mfma_f32_16x16x32_bf16 v[102:105], v[134:137], v[190:193], v[102:105]
	v_mfma_f32_16x16x32_bf16 v[98:101], v[154:157], v[190:193], v[98:101]
	s_setprio 0
	s_barrier
	v_or_b32_e32 v165, 0x1c000, v163
	s_mov_b32 m0, s70
	v_add_u32_e32 v197, 0x1c400, v163
	ds_read_b128 v[206:209], v165
	ds_read_b128 v[210:213], v197
	v_add_u32_e32 v165, 0x1c800, v163
	v_lshl_add_u64 v[222:223], v[222:223], 0, s[76:77]
	v_add_u32_e32 v197, 0x1cc00, v163
	ds_read_b128 v[214:217], v165
	ds_read_b128 v[218:221], v197
	global_load_lds_dwordx4 v[222:223], off
	v_lshl_add_u64 v[222:223], v[224:225], 0, s[76:77]
	s_mov_b32 m0, s71
	s_nop 0
	global_load_lds_dwordx4 v[222:223], off
	s_barrier
	s_waitcnt lgkmcnt(0)
	s_setprio 1
	s_waitcnt lgkmcnt(0)
	v_mfma_f32_16x16x32_bf16 v[62:65], v[206:209], v[158:161], v[62:65]
	v_mfma_f32_16x16x32_bf16 v[58:61], v[214:217], v[158:161], v[58:61]
	v_mfma_f32_16x16x32_bf16 v[54:57], v[206:209], v[170:173], v[54:57]
	v_mfma_f32_16x16x32_bf16 v[46:49], v[214:217], v[170:173], v[46:49]
	v_mfma_f32_16x16x32_bf16 v[50:53], v[206:209], v[178:181], v[50:53]
	v_mfma_f32_16x16x32_bf16 v[42:45], v[214:217], v[178:181], v[42:45]
	v_mfma_f32_16x16x32_bf16 v[38:41], v[206:209], v[186:189], v[38:41]
	v_mfma_f32_16x16x32_bf16 v[34:37], v[214:217], v[186:189], v[34:37]
	v_mfma_f32_16x16x32_bf16 v[62:65], v[210:213], v[166:169], v[62:65]
	v_mfma_f32_16x16x32_bf16 v[58:61], v[218:221], v[166:169], v[58:61]
	v_mfma_f32_16x16x32_bf16 v[54:57], v[210:213], v[174:177], v[54:57]
	v_mfma_f32_16x16x32_bf16 v[46:49], v[218:221], v[174:177], v[46:49]
	v_mfma_f32_16x16x32_bf16 v[50:53], v[210:213], v[182:185], v[50:53]
	v_mfma_f32_16x16x32_bf16 v[42:45], v[218:221], v[182:185], v[42:45]
	v_mfma_f32_16x16x32_bf16 v[38:41], v[210:213], v[190:193], v[38:41]
	v_mfma_f32_16x16x32_bf16 v[34:37], v[218:221], v[190:193], v[34:37]
	s_setprio 0
	s_mov_b32 m0, s78
	v_lshl_add_u64 v[222:223], v[226:227], 0, s[76:77]
	s_barrier
	ds_read_b128 v[158:161], v162 offset:49152
	ds_read_b128 v[166:169], v162 offset:50176
	ds_read_b128 v[170:173], v162 offset:51200
	ds_read_b128 v[174:177], v162 offset:52224
	ds_read_b128 v[178:181], v162 offset:53248
	ds_read_b128 v[182:185], v162 offset:54272
	ds_read_b128 v[186:189], v162 offset:55296
	ds_read_b128 v[190:193], v162 offset:56320
	global_load_lds_dwordx4 v[222:223], off
	v_lshl_add_u64 v[222:223], v[228:229], 0, s[76:77]
	s_mov_b32 m0, s79
	s_nop 0
	global_load_lds_dwordx4 v[222:223], off
	s_barrier
	s_waitcnt lgkmcnt(0)
	s_setprio 1
	s_waitcnt lgkmcnt(0)
	v_mfma_f32_16x16x32_bf16 v[94:97], v[130:133], v[158:161], v[94:97]
	v_mfma_f32_16x16x32_bf16 v[90:93], v[150:153], v[158:161], v[90:93]
	v_mfma_f32_16x16x32_bf16 v[86:89], v[130:133], v[170:173], v[86:89]
	v_mfma_f32_16x16x32_bf16 v[82:85], v[150:153], v[170:173], v[82:85]
	v_mfma_f32_16x16x32_bf16 v[78:81], v[130:133], v[178:181], v[78:81]
	v_mfma_f32_16x16x32_bf16 v[74:77], v[150:153], v[178:181], v[74:77]
	v_mfma_f32_16x16x32_bf16 v[70:73], v[130:133], v[186:189], v[70:73]
	v_mfma_f32_16x16x32_bf16 v[66:69], v[150:153], v[186:189], v[66:69]
	v_mfma_f32_16x16x32_bf16 v[94:97], v[134:137], v[166:169], v[94:97]
	v_mfma_f32_16x16x32_bf16 v[90:93], v[154:157], v[166:169], v[90:93]
	v_mfma_f32_16x16x32_bf16 v[86:89], v[134:137], v[174:177], v[86:89]
	v_mfma_f32_16x16x32_bf16 v[82:85], v[154:157], v[174:177], v[82:85]
	v_mfma_f32_16x16x32_bf16 v[78:81], v[134:137], v[182:185], v[78:81]
	v_mfma_f32_16x16x32_bf16 v[74:77], v[154:157], v[182:185], v[74:77]
	v_mfma_f32_16x16x32_bf16 v[70:73], v[134:137], v[190:193], v[70:73]
	v_mfma_f32_16x16x32_bf16 v[66:69], v[154:157], v[190:193], v[66:69]
	s_setprio 0
	s_barrier
	s_add_u32 s10, s54, 0x80080
	s_addc_u32 s11, s55, 0
	s_mov_b32 m0, s80
	v_lshl_add_u64 v[130:131], s[10:11], 0, v[194:195]
	global_load_lds_dwordx4 v[130:131], off
	v_lshl_add_u64 v[130:131], s[10:11], 0, v[138:139]
	s_mov_b32 m0, s81
	s_nop 0
	global_load_lds_dwordx4 v[130:131], off
	s_waitcnt vmcnt(6)
	s_barrier
	s_setprio 1
	v_mfma_f32_16x16x32_bf16 v[30:33], v[206:209], v[158:161], v[30:33]
	v_mfma_f32_16x16x32_bf16 v[18:21], v[214:217], v[158:161], v[18:21]
	v_mfma_f32_16x16x32_bf16 v[26:29], v[206:209], v[170:173], v[26:29]
	v_mfma_f32_16x16x32_bf16 v[14:17], v[214:217], v[170:173], v[14:17]
	v_mfma_f32_16x16x32_bf16 v[22:25], v[206:209], v[178:181], v[22:25]
	v_mfma_f32_16x16x32_bf16 v[6:9], v[214:217], v[178:181], v[6:9]
	v_mfma_f32_16x16x32_bf16 v[10:13], v[206:209], v[186:189], v[10:13]
	v_mfma_f32_16x16x32_bf16 v[2:5], v[214:217], v[186:189], v[2:5]
	v_mfma_f32_16x16x32_bf16 v[30:33], v[210:213], v[166:169], v[30:33]
	v_mfma_f32_16x16x32_bf16 v[18:21], v[218:221], v[166:169], v[18:21]
	v_mfma_f32_16x16x32_bf16 v[26:29], v[210:213], v[174:177], v[26:29]
	v_mfma_f32_16x16x32_bf16 v[14:17], v[218:221], v[174:177], v[14:17]
	v_mfma_f32_16x16x32_bf16 v[22:25], v[210:213], v[182:185], v[22:25]
	v_mfma_f32_16x16x32_bf16 v[6:9], v[218:221], v[182:185], v[6:9]
	v_mfma_f32_16x16x32_bf16 v[10:13], v[210:213], v[190:193], v[10:13]
	v_mfma_f32_16x16x32_bf16 v[2:5], v[218:221], v[190:193], v[2:5]
	s_setprio 0
	s_add_i32 s29, s29, 2
	s_add_u32 s52, s52, 0x100
	s_addc_u32 s53, s53, 0
	s_add_u32 s5, s5, 0x100
	s_addc_u32 s7, s7, 0
	s_cmp_gt_u32 s29, 29
	s_barrier
	s_cbranch_scc0 .LBB0_504
	v_readlane_b32 s10, v250, 21
	s_cmp_gt_i32 s40, 63
	v_readlane_b32 s11, v250, 22
	s_mov_b64 s[20:21], s[48:49]
	v_readlane_b32 s26, v252, 6
	v_readlane_b32 s27, v252, 7
	s_cselect_b32 s11, s21, s11
	s_cselect_b32 s10, s20, s10
	s_cselect_b32 s53, s3, s27
	s_cselect_b32 s52, s2, s26
	s_sub_i32 s5, s40, 64
	s_cmp_gt_i32 s40, 63
	s_cselect_b32 s54, s5, s40
	s_lshr_b32 s5, s40, 3
	s_mulk_i32 s5, 0x1800
	s_cmp_gt_i32 s40, 63
	s_cselect_b32 s20, 0xc000, s5
	s_lshl_b32 s20, s20, 2
	s_lshl_b32 s7, s28, 10
	s_add_i32 s20, s20, s7
	s_add_i32 s20, s20, 0x6484000
	s_add_u32 s22, s63, s20
	s_addc_u32 s23, s67, 0
	s_lshl_b32 s5, s54, 21
	s_add_i32 s5, s5, s7
	s_add_u32 s10, s10, s5
	s_addc_u32 s11, s11, 0
	s_add_u32 s52, s52, s5
	s_addc_u32 s53, s53, 0
	v_lshlrev_b32_e32 v165, 2, v164
	v_lshl_add_u32 v197, v144, 2, v165
	global_load_dwordx4 v[130:133], v165, s[22:23]
	global_load_dwordx4 v[134:137], v165, s[22:23] offset:16
	global_load_dwordx4 v[150:153], v165, s[22:23] offset:512
	global_load_dwordx4 v[154:157], v165, s[22:23] offset:528
	global_load_dwordx4 v[166:169], v197, s[10:11]
	global_load_dwordx4 v[170:173], v197, s[10:11] offset:16
	s_add_u32 s26, s10, 0x20000
	s_addc_u32 s27, s11, 0
	global_load_dwordx4 v[174:177], v197, s[26:27]
	global_load_dwordx4 v[178:181], v197, s[26:27] offset:16
	s_add_u32 s24, s10, 0x40000
	s_addc_u32 s25, s11, 0
	global_load_dwordx4 v[182:185], v197, s[24:25]
	global_load_dwordx4 v[186:189], v197, s[24:25] offset:16
	s_add_u32 s26, s10, 0x60000
	s_addc_u32 s27, s11, 0
	global_load_dwordx4 v[190:193], v197, s[26:27]
	global_load_dwordx4 v[206:209], v197, s[26:27] offset:16
	s_add_u32 s24, s10, 0x100000
	s_addc_u32 s25, s11, 0
	global_load_dwordx4 v[158:161], v197, s[24:25]
	global_load_dwordx4 v[210:213], v197, s[24:25] offset:16
	s_add_u32 s26, s10, 0x120000
	s_addc_u32 s27, s11, 0
	global_load_dwordx4 v[214:217], v197, s[26:27]
	global_load_dwordx4 v[218:221], v197, s[26:27] offset:16
	s_add_u32 s24, s10, 0x140000
	s_addc_u32 s25, s11, 0
	global_load_dwordx4 v[222:225], v197, s[24:25]
	global_load_dwordx4 v[226:229], v197, s[24:25] offset:16
	s_add_u32 s26, s10, 0x160000
	s_addc_u32 s27, s11, 0
	global_load_dwordx4 v[242:245], v197, s[26:27]
	global_load_dwordx4 v[246:249], v197, s[26:27] offset:16
	s_waitcnt vmcnt(8)
	v_pk_fma_f32 v[126:127], v[126:127], v[130:131], v[166:167]
	v_pk_fma_f32 v[128:129], v[128:129], v[132:133], v[168:169]
	v_pk_fma_f32 v[122:123], v[122:123], v[134:135], v[170:171]
	v_pk_fma_f32 v[124:125], v[124:125], v[136:137], v[172:173]
	v_pk_fma_f32 v[118:119], v[118:119], v[130:131], v[174:175]
	v_pk_fma_f32 v[120:121], v[120:121], v[132:133], v[176:177]
	v_pk_fma_f32 v[114:115], v[114:115], v[134:135], v[178:179]
	v_pk_fma_f32 v[116:117], v[116:117], v[136:137], v[180:181]
	v_pk_fma_f32 v[110:111], v[110:111], v[130:131], v[182:183]
	v_pk_fma_f32 v[112:113], v[112:113], v[132:133], v[184:185]
	v_pk_fma_f32 v[106:107], v[106:107], v[134:135], v[186:187]
	v_pk_fma_f32 v[108:109], v[108:109], v[136:137], v[188:189]
	v_pk_fma_f32 v[102:103], v[102:103], v[130:131], v[190:191]
	v_pk_fma_f32 v[104:105], v[104:105], v[132:133], v[192:193]
	v_pk_fma_f32 v[98:99], v[98:99], v[134:135], v[206:207]
	v_pk_fma_f32 v[100:101], v[100:101], v[136:137], v[208:209]
	global_store_dwordx4 v197, v[126:129], s[52:53]
	global_store_dwordx4 v197, v[122:125], s[52:53] offset:16
	s_add_u32 s26, s52, 0x20000
	s_addc_u32 s27, s53, 0
	global_store_dwordx4 v197, v[118:121], s[26:27]
	global_store_dwordx4 v197, v[114:117], s[26:27] offset:16
	s_add_u32 s24, s52, 0x40000
	s_addc_u32 s25, s53, 0
	global_store_dwordx4 v197, v[110:113], s[24:25]
	global_store_dwordx4 v197, v[106:109], s[24:25] offset:16
	s_add_u32 s26, s52, 0x60000
	s_addc_u32 s27, s53, 0
	global_store_dwordx4 v197, v[102:105], s[26:27]
	global_store_dwordx4 v197, v[98:101], s[26:27] offset:16
	global_load_dwordx4 v[166:169], v197, s[10:11] offset:512
	global_load_dwordx4 v[170:173], v197, s[10:11] offset:528
	s_add_u32 s26, s10, 0x20000
	s_addc_u32 s27, s11, 0
	global_load_dwordx4 v[174:177], v197, s[26:27] offset:512
	global_load_dwordx4 v[178:181], v197, s[26:27] offset:528
	s_add_u32 s24, s10, 0x40000
	s_addc_u32 s25, s11, 0
	global_load_dwordx4 v[182:185], v197, s[24:25] offset:512
	global_load_dwordx4 v[186:189], v197, s[24:25] offset:528
	s_add_u32 s26, s10, 0x60000
	s_addc_u32 s27, s11, 0
	global_load_dwordx4 v[190:193], v197, s[26:27] offset:512
	global_load_dwordx4 v[206:209], v197, s[26:27] offset:528
	s_add_u32 s24, s10, 0x100000
	s_addc_u32 s25, s11, 0
	global_load_dwordx4 v[126:129], v197, s[24:25] offset:512
	global_load_dwordx4 v[122:125], v197, s[24:25] offset:528
	s_add_u32 s26, s10, 0x120000
	s_addc_u32 s27, s11, 0
	global_load_dwordx4 v[118:121], v197, s[26:27] offset:512
	global_load_dwordx4 v[114:117], v197, s[26:27] offset:528
	s_add_u32 s24, s10, 0x140000
	s_addc_u32 s25, s11, 0
	global_load_dwordx4 v[110:113], v197, s[24:25] offset:512
	global_load_dwordx4 v[106:109], v197, s[24:25] offset:528
	s_add_u32 s26, s10, 0x160000
	s_addc_u32 s27, s11, 0
	global_load_dwordx4 v[102:105], v197, s[26:27] offset:512
	global_load_dwordx4 v[98:101], v197, s[26:27] offset:528
	s_waitcnt vmcnt(24)
	v_pk_fma_f32 v[94:95], v[94:95], v[130:131], v[158:159]
	v_pk_fma_f32 v[96:97], v[96:97], v[132:133], v[160:161]
	v_pk_fma_f32 v[90:91], v[90:91], v[134:135], v[210:211]
	v_pk_fma_f32 v[92:93], v[92:93], v[136:137], v[212:213]
	v_pk_fma_f32 v[86:87], v[86:87], v[130:131], v[214:215]
	v_pk_fma_f32 v[88:89], v[88:89], v[132:133], v[216:217]
	v_pk_fma_f32 v[82:83], v[82:83], v[134:135], v[218:219]
	v_pk_fma_f32 v[84:85], v[84:85], v[136:137], v[220:221]
	v_pk_fma_f32 v[78:79], v[78:79], v[130:131], v[222:223]
	v_pk_fma_f32 v[80:81], v[80:81], v[132:133], v[224:225]
	v_pk_fma_f32 v[74:75], v[74:75], v[134:135], v[226:227]
	v_pk_fma_f32 v[76:77], v[76:77], v[136:137], v[228:229]
	v_pk_fma_f32 v[70:71], v[70:71], v[130:131], v[242:243]
	v_pk_fma_f32 v[72:73], v[72:73], v[132:133], v[244:245]
	v_pk_fma_f32 v[66:67], v[66:67], v[134:135], v[246:247]
	v_pk_fma_f32 v[68:69], v[68:69], v[136:137], v[248:249]
	s_add_u32 s24, s52, 0x100000
	s_addc_u32 s25, s53, 0
	global_store_dwordx4 v197, v[94:97], s[24:25]
	global_store_dwordx4 v197, v[90:93], s[24:25] offset:16
	s_add_u32 s26, s52, 0x120000
	s_addc_u32 s27, s53, 0
	global_store_dwordx4 v197, v[86:89], s[26:27]
	global_store_dwordx4 v197, v[82:85], s[26:27] offset:16
	s_add_u32 s24, s52, 0x140000
	s_addc_u32 s25, s53, 0
	global_store_dwordx4 v197, v[78:81], s[24:25]
	global_store_dwordx4 v197, v[74:77], s[24:25] offset:16
	s_add_u32 s26, s52, 0x160000
	s_addc_u32 s27, s53, 0
	global_store_dwordx4 v197, v[70:73], s[26:27]
	global_store_dwordx4 v197, v[66:69], s[26:27] offset:16
	s_waitcnt vmcnt(16)
	v_pk_fma_f32 v[62:63], v[62:63], v[150:151], v[166:167]
	v_pk_fma_f32 v[64:65], v[64:65], v[152:153], v[168:169]
	v_pk_fma_f32 v[58:59], v[58:59], v[154:155], v[170:171]
	v_pk_fma_f32 v[60:61], v[60:61], v[156:157], v[172:173]
	v_pk_fma_f32 v[54:55], v[54:55], v[150:151], v[174:175]
	v_pk_fma_f32 v[56:57], v[56:57], v[152:153], v[176:177]
	v_pk_fma_f32 v[46:47], v[46:47], v[154:155], v[178:179]
	v_pk_fma_f32 v[48:49], v[48:49], v[156:157], v[180:181]
	v_pk_fma_f32 v[50:51], v[50:51], v[150:151], v[182:183]
	v_pk_fma_f32 v[52:53], v[52:53], v[152:153], v[184:185]
	v_pk_fma_f32 v[42:43], v[42:43], v[154:155], v[186:187]
	v_pk_fma_f32 v[44:45], v[44:45], v[156:157], v[188:189]
	v_pk_fma_f32 v[38:39], v[38:39], v[150:151], v[190:191]
	v_pk_fma_f32 v[40:41], v[40:41], v[152:153], v[192:193]
	v_pk_fma_f32 v[34:35], v[34:35], v[154:155], v[206:207]
	v_pk_fma_f32 v[36:37], v[36:37], v[156:157], v[208:209]
	global_store_dwordx4 v197, v[62:65], s[52:53] offset:512
	global_store_dwordx4 v197, v[58:61], s[52:53] offset:528
	s_add_u32 s26, s52, 0x20000
	s_addc_u32 s27, s53, 0
	global_store_dwordx4 v197, v[54:57], s[26:27] offset:512
	global_store_dwordx4 v197, v[46:49], s[26:27] offset:528
	s_add_u32 s24, s52, 0x40000
	s_addc_u32 s25, s53, 0
	global_store_dwordx4 v197, v[50:53], s[24:25] offset:512
	global_store_dwordx4 v197, v[42:45], s[24:25] offset:528
	s_add_u32 s26, s52, 0x60000
	s_addc_u32 s27, s53, 0
	global_store_dwordx4 v197, v[38:41], s[26:27] offset:512
	global_store_dwordx4 v197, v[34:37], s[26:27] offset:528
	s_waitcnt vmcnt(16)
	v_pk_fma_f32 v[30:31], v[30:31], v[150:151], v[126:127]
	v_pk_fma_f32 v[32:33], v[32:33], v[152:153], v[128:129]
	v_pk_fma_f32 v[18:19], v[18:19], v[154:155], v[122:123]
	v_pk_fma_f32 v[20:21], v[20:21], v[156:157], v[124:125]
	v_pk_fma_f32 v[26:27], v[26:27], v[150:151], v[118:119]
	v_pk_fma_f32 v[28:29], v[28:29], v[152:153], v[120:121]
	v_pk_fma_f32 v[14:15], v[14:15], v[154:155], v[114:115]
	v_pk_fma_f32 v[16:17], v[16:17], v[156:157], v[116:117]
	v_pk_fma_f32 v[22:23], v[22:23], v[150:151], v[110:111]
	v_pk_fma_f32 v[24:25], v[24:25], v[152:153], v[112:113]
	v_pk_fma_f32 v[6:7], v[6:7], v[154:155], v[106:107]
	v_pk_fma_f32 v[8:9], v[8:9], v[156:157], v[108:109]
	v_pk_fma_f32 v[10:11], v[10:11], v[150:151], v[102:103]
	v_pk_fma_f32 v[12:13], v[12:13], v[152:153], v[104:105]
	v_pk_fma_f32 v[2:3], v[2:3], v[154:155], v[98:99]
	v_pk_fma_f32 v[4:5], v[4:5], v[156:157], v[100:101]
	s_add_u32 s24, s52, 0x100000
	s_addc_u32 s25, s53, 0
	global_store_dwordx4 v197, v[30:33], s[24:25] offset:512
	global_store_dwordx4 v197, v[18:21], s[24:25] offset:528
	s_add_u32 s26, s52, 0x120000
	s_addc_u32 s27, s53, 0
	global_store_dwordx4 v197, v[26:29], s[26:27] offset:512
	global_store_dwordx4 v197, v[14:17], s[26:27] offset:528
	s_add_u32 s24, s52, 0x140000
	s_addc_u32 s25, s53, 0
	global_store_dwordx4 v197, v[22:25], s[24:25] offset:512
	global_store_dwordx4 v197, v[6:9], s[24:25] offset:528
	s_add_u32 s26, s52, 0x160000
	s_addc_u32 s27, s53, 0
	global_store_dwordx4 v197, v[10:13], s[26:27] offset:512
	global_store_dwordx4 v197, v[2:5], s[26:27] offset:528
	s_and_b64 vcc, exec, s[0:1]
	s_mov_b32 s40, s6
	s_mov_b32 s28, s4
	s_mov_b64 s[54:55], s[34:35]
	s_mov_b64 s[52:53], s[8:9]
	s_cbranch_vccz .LBB0_501
	s_waitcnt vmcnt(0)
	v_readlane_b32 s28, v250, 12
	v_readlane_b32 s26, v250, 15
	s_cmpk_gt_u32 s12, 0xff
	v_readlane_b32 s29, v250, 13
	v_readlane_b32 s27, v250, 16
	s_mov_b32 s70, 0x800000
	v_readlane_b32 s79, v250, 18
	s_cbranch_scc1 .LBB0_508
	s_barrier
